# out-proj and FFN-down GEMM loops: first K iteration peeled with C=0, the 64 accumulator-zeroing v_mov_b64 per phase removed
# speedup vs baseline: 1.0006x; 1.0006x over previous
; #define PG8_STAGE(bufoff, gbase, voff) do { _Pragma("unroll") for (int _i = 0; _i < 2; ++_i) \
;         __builtin_amdgcn_global_load_lds((const unsigned*)((const char*)(gbase) + (voff)[_i]), (LAS unsigned*)(lds + (bufoff) + ldsw + _i * 8192), 16, 0, 0); } while (0)
; #define PG8_WAIT_V(n) asm volatile("s_waitcnt vmcnt(" #n ")" ::: "memory")
; #define PG8_BAR __builtin_amdgcn_s_barrier()
; template <class Epi>
; __device__ __forceinline__ void gemm_phase(LAS unsigned char* lds, const Gemm g, const int G, const int cidx, const Epi& E) {
;     ...
;     f32x4 acc[2][2][4][2];
; #pragma unroll
;     for (int a = 0; a < 2; ++a)
; #pragma unroll
;         for (int b = 0; b < 2; ++b)
; #pragma unroll
;             for (int m = 0; m < 4; ++m)
; #pragma unroll
;                 for (int n = 0; n < 2; ++n) acc[a][b][m][n] = ZERO4;
;     bf16x8 At[4][2], B0[2][2], B1[2][2];
;     const char* cA = PG8_ABASE(cur); const char* cB = (const char*)g.Bt + (size_t)cur.pn * tstep;
;     PG8_STAGE(PG8_SB(0, 0), cB, voffB); PG8_STAGE(PG8_SB(0, 1), cB + hstep, voffB); PG8_STAGE(PG8_SA(0, 0), cA, voffA); PG8_STAGE(PG8_SA(0, 1), cA + hstep, voffA);
;     if (wr == 1) PG8_BAR;
;     PG8_WAIT_V(2); PG8_BAR;
;     PG8_STAGE(PG8_SB(1, 0), cB + kstep, voffB); PG8_STAGE(PG8_SA(1, 0), cA + kstep, voffA); PG8_STAGE(PG8_SB(1, 1), cB + hstep + kstep, voffB);
;     PG8_WAIT_V(6); PG8_BAR;
.LBB0_208:
	v_mov_b32_e32 v147, v2
	v_and_b32_e32 v145, 15, v156
	v_and_b32_e32 v9, 48, v156
	v_lshlrev_b32_e32 v18, 2, v156
	v_lshl_add_u64 v[10:11], s[70:71], 0, v[146:147]
	v_mov_b32_e32 v149, v2
	s_and_b32 s95, s21, 3
	s_lshl_b32 s0, s23, 13
	v_lshl_or_b32 v9, v145, 6, v9
	v_and_b32_e32 v18, 32, v18
	v_lshl_add_u64 v[12:13], s[70:71], 0, v[148:149]
	v_bitop3_b32 v19, v9, s0, v18 bitop3:0xde
	s_lshl_b32 s0, s95, 12
	s_add_i32 m0, s19, 0x18000
	v_lshl_add_u64 v[10:11], v[10:11], 0, s[46:47]
	v_lshl_add_u64 v[14:15], s[8:9], 0, v[146:147]
	s_lshl_b32 s94, s23, 6
	v_bitop3_b32 v158, v9, s0, v18 bitop3:0xde
	s_waitcnt vmcnt(2)
	s_barrier
	global_load_lds_dwordx4 v[10:11], off
	v_lshl_add_u64 v[10:11], v[12:13], 0, s[46:47]
	s_add_i32 m0, s19, 0x1a000
	s_add_i32 s0, s19, 0x8000
	s_add_i32 s2, s19, 0xa000
	v_lshl_add_u64 v[16:17], s[8:9], 0, v[148:149]
	s_sext_i32_i8 s20, s4
	global_load_lds_dwordx4 v[10:11], off
	v_lshl_add_u64 v[10:11], v[14:15], 0, s[46:47]
	s_mov_b32 m0, s0
	s_add_u32 s4, s70, 0x40080
	global_load_lds_dwordx4 v[10:11], off
	v_lshl_add_u64 v[10:11], v[16:17], 0, s[46:47]
	s_mov_b32 m0, s2
	s_addc_u32 s5, s71, 0
	global_load_lds_dwordx4 v[10:11], off
	s_add_i32 m0, s19, 0x1c000
	v_lshl_add_u64 v[10:11], s[4:5], 0, v[146:147]
	global_load_lds_dwordx4 v[10:11], off
	v_lshl_add_u64 v[10:11], s[4:5], 0, v[148:149]
	s_add_i32 m0, s19, 0x1e000
	v_lshlrev_b32_e32 v5, 13, v5
	global_load_lds_dwordx4 v[10:11], off
	v_lshlrev_b32_e32 v0, 13, v0
	v_and_b32_e32 v5, 0x7fffc000, v5
	v_and_b32_e32 v0, 0x7fffc000, v0
	v_lshl_add_u32 v5, v6, 10, v5
	v_lshl_add_u32 v0, v1, 10, v0
	s_waitcnt vmcnt(6)
	v_or_b32_e32 v5, v5, v7
	v_or_b32_e32 v0, v0, v3
	v_mov_b32_e32 v3, v2
	v_add_lshl_u32 v150, v5, v8, 1
	v_add_lshl_u32 v152, v0, v4, 1
	v_mov_b32_e32 v0, v2
	v_mov_b32_e32 v1, v2
	v_add_u32_e32 v159, 0, v19
	v_or_b32_e32 v157, s94, v145
	v_mov_b32_e32 v151, v2
	v_mov_b32_e32 v153, v2
	s_mov_b32 s38, 0
	s_barrier

; #define PG8_STAGE(bufoff, gbase, voff) do { _Pragma("unroll") for (int _i = 0; _i < 2; ++_i) \
;         __builtin_amdgcn_global_load_lds((const unsigned*)((const char*)(gbase) + (voff)[_i]), (LAS unsigned*)(lds + (bufoff) + ldsw + _i * 8192), 16, 0, 0); } while (0)
; #define PG8_LDA(dst, b, h) do { _Pragma("unroll") for (int m = 0; m < 4; ++m) _Pragma("unroll") for (int k = 0; k < 2; ++k) dst[m][k] = *(const LAS bf16x8*)(lds + PG8_SA(b, h) + aoff + m * 2048 + k * 1024); } while (0)
; #define PG8_LDB(dst, b, h) do { _Pragma("unroll") for (int n = 0; n < 2; ++n) _Pragma("unroll") for (int k = 0; k < 2; ++k) dst[n][k] = *(const LAS bf16x8*)(lds + PG8_SB(b, h) + boff + n * 2048 + k * 1024); } while (0)
; #define PG8_MMA(ai, bj, At, Bt) do { __builtin_amdgcn_s_setprio(1); _Pragma("unroll") for (int m = 0; m < 4; ++m) _Pragma("unroll") for (int n = 0; n < 2; ++n) _Pragma("unroll") for (int k = 0; k < 2; ++k) \
;         acc[ai][bj][m][n] = __builtin_amdgcn_mfma_f32_16x16x32_bf16(Bt[n][k], At[m][k], acc[ai][bj][m][n], 0, 0, 0); __builtin_amdgcn_s_setprio(0); } while (0)
; #define PG8_WAIT_V(n) asm volatile("s_waitcnt vmcnt(" #n ")" ::: "memory")
; #define PG8_WAIT_L(n) asm volatile("s_waitcnt lgkmcnt(" #n ")" ::: "memory")
; #define PG8_BAR __builtin_amdgcn_s_barrier()
; #define PG8_SCHED __builtin_amdgcn_sched_barrier(0)
; template <class Epi>
; __device__ __forceinline__ void gemm_phase(LAS unsigned char* lds, const Gemm g, const int G, const int cidx, const Epi& E) {
;     ...
;         for (int t = 0; t < nt; t += 2) {
;             const bool last = (t == nt - 2);
;             const char* a1 = cA + (size_t)(t + 1) * kstep;
;             const char* a2 = last ? nA : cA + (size_t)(t + 2) * kstep; const char* b2 = last ? nB : cB + (size_t)(t + 2) * kstep;
;             const char* a3 = a2 + kstep; const char* b3 = b2 + kstep;
;             PG8_LDB(B0, 0, 0); PG8_LDB(B1, 0, 1); PG8_SCHED; PG8_LDA(At, 0, 0); PG8_STAGE(PG8_SA(1, 1), a1 + hstep, voffA);
;             PG8_WAIT_V(8); PG8_WAIT_L(0); PG8_BAR; PG8_MMA(0, 0, At, B0); PG8_MMA(0, 1, At, B1); PG8_BAR; PG8_SCHED;
;             PG8_LDA(At, 0, 1); PG8_STAGE(PG8_SB(0, 0), b2, voffB); PG8_STAGE(PG8_SB(0, 1), b2 + hstep, voffB); PG8_STAGE(PG8_SA(0, 0), a2, voffA);
;             PG8_WAIT_V(8); PG8_WAIT_L(0); PG8_BAR; PG8_MMA(1, 0, At, B0); PG8_MMA(1, 1, At, B1); PG8_BAR; PG8_SCHED;
.LBB0_215:
	s_add_u32 s43, s70, 0x100
	s_addc_u32 s44, s71, 0
	s_ashr_i32 s31, s30, 31
	s_lshl_b64 s[34:35], s[30:31], 19
	s_add_u32 s36, s12, s34
	s_addc_u32 s37, s13, s35
	s_and_b64 s[34:35], s[6:7], exec
	s_cselect_b32 s31, s37, s9
	s_cselect_b32 s45, s36, s8
	s_ashr_i32 s29, s28, 31
	s_lshl_b64 s[34:35], s[28:29], 19
	s_add_u32 s34, s17, s34
	s_addc_u32 s35, s22, s35
	s_and_b64 s[72:73], s[6:7], exec
	s_cselect_b32 s29, s35, s71
	s_cselect_b32 s68, s34, s70
	s_add_u32 s70, s8, 0x40080
	s_addc_u32 s71, s9, 0
	v_lshl_add_u64 v[0:1], s[70:71], 0, v[150:151]
	v_lshl_add_u64 v[154:155], s[70:71], 0, v[152:153]
	s_mov_b32 s77, -2
	s_mov_b64 s[70:71], 0
	s_add_u32 s72, s8, s70
	s_addc_u32 s73, s9, s71
	s_add_u32 s72, s72, 0x100
	s_addc_u32 s73, s73, 0
	s_add_u32 s83, s43, s70
	s_addc_u32 s86, s44, s71
	s_add_i32 s87, 0, 0x10000
	s_cmpk_eq_i32 s70, 0x700
	s_cselect_b32 s75, s31, s73
	s_cselect_b32 s74, s45, s72
	v_add_u32_e32 v3, s87, v158
	s_cselect_b32 s73, s29, s86
	s_cselect_b32 s72, s68, s83
	s_add_i32 s83, 0, 0x14000
	ds_read_b128 v[132:135], v3
	ds_read_b128 v[140:143], v3 offset:1024
	ds_read_b128 v[160:163], v3 offset:2048
	ds_read_b128 v[164:167], v3 offset:3072
	v_add_u32_e32 v3, s83, v158
	ds_read_b128 v[168:171], v3
	ds_read_b128 v[172:175], v3 offset:1024
	ds_read_b128 v[176:179], v3 offset:2048
	ds_read_b128 v[180:183], v3 offset:3072
	v_lshl_add_u64 v[200:201], v[154:155], 0, s[70:71]
	s_add_i32 m0, s19, 0xc000
	ds_read_b128 v[184:187], v159
	ds_read_b128 v[188:191], v159 offset:1024
	ds_read_b128 v[192:195], v159 offset:2048
	ds_read_b128 v[196:199], v159 offset:3072
	ds_read_b128 v[214:217], v159 offset:4096
	ds_read_b128 v[218:221], v159 offset:5120
	ds_read_b128 v[222:225], v159 offset:6144
	ds_read_b128 v[226:229], v159 offset:7168
	global_load_lds_dwordx4 v[200:201], off
	v_lshl_add_u64 v[200:201], v[0:1], 0, s[70:71]
	s_add_i32 m0, s19, 0xe000
	s_nop 0
	global_load_lds_dwordx4 v[200:201], off
	s_waitcnt vmcnt(8)
	s_waitcnt lgkmcnt(0)
	s_barrier
	s_setprio 1
	s_waitcnt lgkmcnt(0)
	v_mfma_f32_16x16x32_bf16 v[64:67], v[132:135], v[184:187], 0
	v_mfma_f32_16x16x32_bf16 v[72:75], v[160:163], v[184:187], 0
	v_mfma_f32_16x16x32_bf16 v[92:95], v[132:135], v[192:195], 0
	v_mfma_f32_16x16x32_bf16 v[96:99], v[160:163], v[192:195], 0
	v_mfma_f32_16x16x32_bf16 v[116:119], v[132:135], v[214:217], 0
	v_mfma_f32_16x16x32_bf16 v[124:127], v[160:163], v[214:217], 0
	v_mfma_f32_16x16x32_bf16 v[112:115], v[132:135], v[222:225], 0
	v_mfma_f32_16x16x32_bf16 v[100:103], v[160:163], v[222:225], 0
	v_mfma_f32_16x16x32_bf16 v[64:67], v[140:143], v[188:191], v[64:67]
	v_mfma_f32_16x16x32_bf16 v[72:75], v[164:167], v[188:191], v[72:75]
	v_mfma_f32_16x16x32_bf16 v[92:95], v[140:143], v[196:199], v[92:95]
	v_mfma_f32_16x16x32_bf16 v[96:99], v[164:167], v[196:199], v[96:99]
	v_mfma_f32_16x16x32_bf16 v[116:119], v[140:143], v[218:221], v[116:119]
	v_mfma_f32_16x16x32_bf16 v[124:127], v[164:167], v[218:221], v[124:127]
	v_mfma_f32_16x16x32_bf16 v[112:115], v[140:143], v[226:229], v[112:115]
	v_mfma_f32_16x16x32_bf16 v[100:103], v[164:167], v[226:229], v[100:103]
	s_setprio 0
	s_setprio 1
	v_mfma_f32_16x16x32_bf16 v[76:79], v[168:171], v[184:187], 0
	v_mfma_f32_16x16x32_bf16 v[84:87], v[176:179], v[184:187], 0
	v_mfma_f32_16x16x32_bf16 v[104:107], v[168:171], v[192:195], 0
	v_mfma_f32_16x16x32_bf16 v[108:111], v[176:179], v[192:195], 0
	v_mfma_f32_16x16x32_bf16 v[128:131], v[168:171], v[214:217], 0
	v_mfma_f32_16x16x32_bf16 v[120:123], v[176:179], v[214:217], 0
	v_mfma_f32_16x16x32_bf16 v[88:91], v[168:171], v[222:225], 0
	v_mfma_f32_16x16x32_bf16 v[80:83], v[176:179], v[222:225], 0
	v_mfma_f32_16x16x32_bf16 v[76:79], v[172:175], v[188:191], v[76:79]
	v_mfma_f32_16x16x32_bf16 v[84:87], v[180:183], v[188:191], v[84:87]
	v_mfma_f32_16x16x32_bf16 v[104:107], v[172:175], v[196:199], v[104:107]
	v_mfma_f32_16x16x32_bf16 v[108:111], v[180:183], v[196:199], v[108:111]
	v_mfma_f32_16x16x32_bf16 v[128:131], v[172:175], v[218:221], v[128:131]
	v_mfma_f32_16x16x32_bf16 v[120:123], v[180:183], v[218:221], v[120:123]
	v_mfma_f32_16x16x32_bf16 v[88:91], v[172:175], v[226:229], v[88:91]
	v_mfma_f32_16x16x32_bf16 v[80:83], v[180:183], v[226:229], v[80:83]
	s_setprio 0
	s_barrier
	s_add_i32 s86, s87, s40
	v_lshl_add_u64 v[200:201], s[72:73], 0, v[146:147]
	s_mov_b32 m0, s86
	ds_read_b128 v[184:187], v159 offset:16384
	ds_read_b128 v[188:191], v159 offset:17408
	ds_read_b128 v[192:195], v159 offset:18432
	ds_read_b128 v[196:199], v159 offset:19456
	ds_read_b128 v[214:217], v159 offset:20480
	ds_read_b128 v[218:221], v159 offset:21504
	ds_read_b128 v[222:225], v159 offset:22528
	ds_read_b128 v[226:229], v159 offset:23552
	global_load_lds_dwordx4 v[200:201], off
	s_add_i32 m0, s86, 0x2000
	s_add_u32 s86, s72, 0x40000
	v_lshl_add_u64 v[230:231], s[72:73], 0, v[148:149]
	s_addc_u32 s87, s73, 0
	s_add_i32 s83, s83, s40
	global_load_lds_dwordx4 v[230:231], off
	v_lshl_add_u64 v[232:233], s[86:87], 0, v[146:147]
	s_mov_b32 m0, s83
	v_lshl_add_u64 v[234:235], s[74:75], 0, v[148:149]
	global_load_lds_dwordx4 v[232:233], off
	v_lshl_add_u64 v[232:233], s[86:87], 0, v[148:149]
	s_add_i32 m0, s83, 0x2000
	s_nop 0
	global_load_lds_dwordx4 v[232:233], off
	v_lshl_add_u64 v[232:233], s[74:75], 0, v[146:147]
	s_mov_b32 m0, s19
	s_nop 0
	global_load_lds_dwordx4 v[232:233], off
	s_mov_b32 m0, s76
	s_nop 0
	global_load_lds_dwordx4 v[234:235], off
	s_waitcnt vmcnt(8)
	s_waitcnt lgkmcnt(0)
	s_barrier
; #define PG8_STAGE(bufoff, gbase, voff) do { _Pragma("unroll") for (int _i = 0; _i < 2; ++_i) \
;         __builtin_amdgcn_global_load_lds((const unsigned*)((const char*)(gbase) + (voff)[_i]), (LAS unsigned*)(lds + (bufoff) + ldsw + _i * 8192), 16, 0, 0); } while (0)
; #define PG8_LDA(dst, b, h) do { _Pragma("unroll") for (int m = 0; m < 4; ++m) _Pragma("unroll") for (int k = 0; k < 2; ++k) dst[m][k] = *(const LAS bf16x8*)(lds + PG8_SA(b, h) + aoff + m * 2048 + k * 1024); } while (0)
; #define PG8_LDB(dst, b, h) do { _Pragma("unroll") for (int n = 0; n < 2; ++n) _Pragma("unroll") for (int k = 0; k < 2; ++k) dst[n][k] = *(const LAS bf16x8*)(lds + PG8_SB(b, h) + boff + n * 2048 + k * 1024); } while (0)
; #define PG8_MMA(ai, bj, At, Bt) do { __builtin_amdgcn_s_setprio(1); _Pragma("unroll") for (int m = 0; m < 4; ++m) _Pragma("unroll") for (int n = 0; n < 2; ++n) _Pragma("unroll") for (int k = 0; k < 2; ++k) \
;         acc[ai][bj][m][n] = __builtin_amdgcn_mfma_f32_16x16x32_bf16(Bt[n][k], At[m][k], acc[ai][bj][m][n], 0, 0, 0); __builtin_amdgcn_s_setprio(0); } while (0)
; #define PG8_WAIT_V(n) asm volatile("s_waitcnt vmcnt(" #n ")" ::: "memory")
; #define PG8_WAIT_L(n) asm volatile("s_waitcnt lgkmcnt(" #n ")" ::: "memory")
; #define PG8_BAR __builtin_amdgcn_s_barrier()
; #define PG8_SCHED __builtin_amdgcn_sched_barrier(0)
; template <class Epi>
; __device__ __forceinline__ void gemm_phase(LAS unsigned char* lds, const Gemm g, const int G, const int cidx, const Epi& E) {
;     ...
;             PG8_WAIT_V(8); PG8_WAIT_L(0); PG8_BAR; PG8_MMA(1, 0, At, B0); PG8_MMA(1, 1, At, B1); PG8_BAR; PG8_SCHED;
;             PG8_LDB(B0, 1, 0); PG8_LDB(B1, 1, 1); PG8_SCHED; PG8_LDA(At, 1, 0); PG8_STAGE(PG8_SA(0, 1), a2 + hstep, voffA);
;             PG8_WAIT_V(8); PG8_WAIT_L(0); PG8_BAR; PG8_MMA(0, 0, At, B0); PG8_MMA(0, 1, At, B1); PG8_BAR; PG8_SCHED;
	s_setprio 1
	s_waitcnt lgkmcnt(0)
	v_mfma_f32_16x16x32_bf16 v[68:71], v[132:135], v[184:187], 0
	v_mfma_f32_16x16x32_bf16 v[60:63], v[160:163], v[184:187], 0
	v_mfma_f32_16x16x32_bf16 v[48:51], v[132:135], v[192:195], 0
	v_mfma_f32_16x16x32_bf16 v[44:47], v[160:163], v[192:195], 0
	v_mfma_f32_16x16x32_bf16 v[32:35], v[132:135], v[214:217], 0
	v_mfma_f32_16x16x32_bf16 v[28:31], v[160:163], v[214:217], 0
	v_mfma_f32_16x16x32_bf16 v[16:19], v[132:135], v[222:225], 0
	v_mfma_f32_16x16x32_bf16 v[12:15], v[160:163], v[222:225], 0
	v_mfma_f32_16x16x32_bf16 v[68:71], v[140:143], v[188:191], v[68:71]
	v_mfma_f32_16x16x32_bf16 v[60:63], v[164:167], v[188:191], v[60:63]
	v_mfma_f32_16x16x32_bf16 v[48:51], v[140:143], v[196:199], v[48:51]
	v_mfma_f32_16x16x32_bf16 v[44:47], v[164:167], v[196:199], v[44:47]
	v_mfma_f32_16x16x32_bf16 v[32:35], v[140:143], v[218:221], v[32:35]
	v_mfma_f32_16x16x32_bf16 v[28:31], v[164:167], v[218:221], v[28:31]
	v_mfma_f32_16x16x32_bf16 v[16:19], v[140:143], v[226:229], v[16:19]
	v_mfma_f32_16x16x32_bf16 v[12:15], v[164:167], v[226:229], v[12:15]
	s_setprio 0
	s_setprio 1
	v_mfma_f32_16x16x32_bf16 v[56:59], v[168:171], v[184:187], 0
	v_mfma_f32_16x16x32_bf16 v[52:55], v[176:179], v[184:187], 0
	v_mfma_f32_16x16x32_bf16 v[40:43], v[168:171], v[192:195], 0
	v_mfma_f32_16x16x32_bf16 v[36:39], v[176:179], v[192:195], 0
	v_mfma_f32_16x16x32_bf16 v[24:27], v[168:171], v[214:217], 0
	v_mfma_f32_16x16x32_bf16 v[20:23], v[176:179], v[214:217], 0
	v_mfma_f32_16x16x32_bf16 v[8:11], v[168:171], v[222:225], 0
	v_mfma_f32_16x16x32_bf16 v[4:7], v[176:179], v[222:225], 0
	v_mfma_f32_16x16x32_bf16 v[56:59], v[172:175], v[188:191], v[56:59]
	v_mfma_f32_16x16x32_bf16 v[52:55], v[180:183], v[188:191], v[52:55]
	v_mfma_f32_16x16x32_bf16 v[40:43], v[172:175], v[196:199], v[40:43]
	v_mfma_f32_16x16x32_bf16 v[36:39], v[180:183], v[196:199], v[36:39]
	v_mfma_f32_16x16x32_bf16 v[24:27], v[172:175], v[218:221], v[24:27]
	v_mfma_f32_16x16x32_bf16 v[20:23], v[180:183], v[218:221], v[20:23]
	v_mfma_f32_16x16x32_bf16 v[8:11], v[172:175], v[226:229], v[8:11]
	v_mfma_f32_16x16x32_bf16 v[4:7], v[180:183], v[226:229], v[4:7]
	s_setprio 0
	s_barrier
	s_add_i32 s83, 0, 0x18000
	v_add_u32_e32 v3, s83, v158
	s_add_i32 s86, 0, 0x1c000
	ds_read_b128 v[132:135], v3
	ds_read_b128 v[140:143], v3 offset:1024
	ds_read_b128 v[160:163], v3 offset:2048
	ds_read_b128 v[164:167], v3 offset:3072
	v_add_u32_e32 v3, s86, v158
	ds_read_b128 v[168:171], v3
	ds_read_b128 v[172:175], v3 offset:1024
	ds_read_b128 v[176:179], v3 offset:2048
	ds_read_b128 v[180:183], v3 offset:3072
	s_add_u32 s74, s74, 0x40000
	s_addc_u32 s75, s75, 0
	s_mov_b32 m0, s84
	v_lshl_add_u64 v[236:237], s[74:75], 0, v[146:147]
	ds_read_b128 v[184:187], v159 offset:32768
	ds_read_b128 v[188:191], v159 offset:33792
	ds_read_b128 v[192:195], v159 offset:34816
	ds_read_b128 v[196:199], v159 offset:35840
	ds_read_b128 v[214:217], v159 offset:36864
	ds_read_b128 v[218:221], v159 offset:37888
	ds_read_b128 v[222:225], v159 offset:38912
	ds_read_b128 v[226:229], v159 offset:39936
	global_load_lds_dwordx4 v[236:237], off
	v_lshl_add_u64 v[236:237], s[74:75], 0, v[148:149]
	s_mov_b32 m0, s97
	s_nop 0
	global_load_lds_dwordx4 v[236:237], off
	s_waitcnt vmcnt(8)
	s_waitcnt lgkmcnt(0)
	s_barrier
	s_setprio 1
	s_waitcnt lgkmcnt(0)
	v_mfma_f32_16x16x32_bf16 v[64:67], v[132:135], v[184:187], v[64:67]
	v_mfma_f32_16x16x32_bf16 v[72:75], v[160:163], v[184:187], v[72:75]
	v_mfma_f32_16x16x32_bf16 v[92:95], v[132:135], v[192:195], v[92:95]
	v_mfma_f32_16x16x32_bf16 v[96:99], v[160:163], v[192:195], v[96:99]
	v_mfma_f32_16x16x32_bf16 v[116:119], v[132:135], v[214:217], v[116:119]
	v_mfma_f32_16x16x32_bf16 v[124:127], v[160:163], v[214:217], v[124:127]
	v_mfma_f32_16x16x32_bf16 v[112:115], v[132:135], v[222:225], v[112:115]
	v_mfma_f32_16x16x32_bf16 v[100:103], v[160:163], v[222:225], v[100:103]
	v_mfma_f32_16x16x32_bf16 v[64:67], v[140:143], v[188:191], v[64:67]
	v_mfma_f32_16x16x32_bf16 v[72:75], v[164:167], v[188:191], v[72:75]
	v_mfma_f32_16x16x32_bf16 v[92:95], v[140:143], v[196:199], v[92:95]
	v_mfma_f32_16x16x32_bf16 v[96:99], v[164:167], v[196:199], v[96:99]
	v_mfma_f32_16x16x32_bf16 v[116:119], v[140:143], v[218:221], v[116:119]
	v_mfma_f32_16x16x32_bf16 v[124:127], v[164:167], v[218:221], v[124:127]
	v_mfma_f32_16x16x32_bf16 v[112:115], v[140:143], v[226:229], v[112:115]
	v_mfma_f32_16x16x32_bf16 v[100:103], v[164:167], v[226:229], v[100:103]
	s_setprio 0
	s_setprio 1
	v_mfma_f32_16x16x32_bf16 v[76:79], v[168:171], v[184:187], v[76:79]
	v_mfma_f32_16x16x32_bf16 v[84:87], v[176:179], v[184:187], v[84:87]
	v_mfma_f32_16x16x32_bf16 v[104:107], v[168:171], v[192:195], v[104:107]
	v_mfma_f32_16x16x32_bf16 v[108:111], v[176:179], v[192:195], v[108:111]
	v_mfma_f32_16x16x32_bf16 v[128:131], v[168:171], v[214:217], v[128:131]
	v_mfma_f32_16x16x32_bf16 v[120:123], v[176:179], v[214:217], v[120:123]
	v_mfma_f32_16x16x32_bf16 v[88:91], v[168:171], v[222:225], v[88:91]
	v_mfma_f32_16x16x32_bf16 v[80:83], v[176:179], v[222:225], v[80:83]
	v_mfma_f32_16x16x32_bf16 v[76:79], v[172:175], v[188:191], v[76:79]
	v_mfma_f32_16x16x32_bf16 v[84:87], v[180:183], v[188:191], v[84:87]
	v_mfma_f32_16x16x32_bf16 v[104:107], v[172:175], v[196:199], v[104:107]
	v_mfma_f32_16x16x32_bf16 v[108:111], v[180:183], v[196:199], v[108:111]
	v_mfma_f32_16x16x32_bf16 v[128:131], v[172:175], v[218:221], v[128:131]
	v_mfma_f32_16x16x32_bf16 v[120:123], v[180:183], v[218:221], v[120:123]
	v_mfma_f32_16x16x32_bf16 v[88:91], v[172:175], v[226:229], v[88:91]
	v_mfma_f32_16x16x32_bf16 v[80:83], v[180:183], v[226:229], v[80:83]
	s_setprio 0
	s_barrier
; #define PG8_STAGE(bufoff, gbase, voff) do { _Pragma("unroll") for (int _i = 0; _i < 2; ++_i) \
;         __builtin_amdgcn_global_load_lds((const unsigned*)((const char*)(gbase) + (voff)[_i]), (LAS unsigned*)(lds + (bufoff) + ldsw + _i * 8192), 16, 0, 0); } while (0)
; #define PG8_LDA(dst, b, h) do { _Pragma("unroll") for (int m = 0; m < 4; ++m) _Pragma("unroll") for (int k = 0; k < 2; ++k) dst[m][k] = *(const LAS bf16x8*)(lds + PG8_SA(b, h) + aoff + m * 2048 + k * 1024); } while (0)
; #define PG8_MMA(ai, bj, At, Bt) do { __builtin_amdgcn_s_setprio(1); _Pragma("unroll") for (int m = 0; m < 4; ++m) _Pragma("unroll") for (int n = 0; n < 2; ++n) _Pragma("unroll") for (int k = 0; k < 2; ++k) \
;         acc[ai][bj][m][n] = __builtin_amdgcn_mfma_f32_16x16x32_bf16(Bt[n][k], At[m][k], acc[ai][bj][m][n], 0, 0, 0); __builtin_amdgcn_s_setprio(0); } while (0)
; #define PG8_WAIT_V(n) asm volatile("s_waitcnt vmcnt(" #n ")" ::: "memory")
; #define PG8_WAIT_L(n) asm volatile("s_waitcnt lgkmcnt(" #n ")" ::: "memory")
; #define PG8_BAR __builtin_amdgcn_s_barrier()
; #define PG8_SCHED __builtin_amdgcn_sched_barrier(0)
; template <class Epi>
; __device__ __forceinline__ void gemm_phase(LAS unsigned char* lds, const Gemm g, const int G, const int cidx, const Epi& E) {
;     ...
;             PG8_LDA(At, 1, 1); PG8_STAGE(PG8_SB(1, 0), b3, voffB); PG8_STAGE(PG8_SB(1, 1), b3 + hstep, voffB); PG8_STAGE(PG8_SA(1, 0), a3, voffA);
;             PG8_WAIT_V(8); PG8_WAIT_L(0); PG8_BAR; PG8_MMA(1, 0, At, B0); PG8_MMA(1, 1, At, B1); PG8_BAR; PG8_SCHED;
	s_add_i32 s74, s83, s40
	v_lshl_add_u64 v[200:201], v[200:201], 0, s[46:47]
	s_mov_b32 m0, s74
	ds_read_b128 v[184:187], v159 offset:49152
	ds_read_b128 v[188:191], v159 offset:50176
	ds_read_b128 v[192:195], v159 offset:51200
	ds_read_b128 v[196:199], v159 offset:52224
	ds_read_b128 v[214:217], v159 offset:53248
	ds_read_b128 v[218:221], v159 offset:54272
	ds_read_b128 v[222:225], v159 offset:55296
	ds_read_b128 v[226:229], v159 offset:56320
	global_load_lds_dwordx4 v[200:201], off
	s_add_i32 m0, s74, 0x2000
	s_add_u32 s72, s72, 0x40080
	v_lshl_add_u64 v[200:201], v[230:231], 0, s[46:47]
	s_addc_u32 s73, s73, 0
	s_add_i32 s74, s86, s40
	global_load_lds_dwordx4 v[200:201], off
	v_lshl_add_u64 v[200:201], s[72:73], 0, v[146:147]
	s_mov_b32 m0, s74
	s_nop 0
	global_load_lds_dwordx4 v[200:201], off
	v_lshl_add_u64 v[200:201], s[72:73], 0, v[148:149]
	s_add_i32 m0, s74, 0x2000
	s_nop 0
	global_load_lds_dwordx4 v[200:201], off
	v_lshl_add_u64 v[200:201], v[232:233], 0, s[46:47]
	s_mov_b32 m0, s0
	s_nop 0
	global_load_lds_dwordx4 v[200:201], off
	v_lshl_add_u64 v[200:201], v[234:235], 0, s[46:47]
	s_mov_b32 m0, s2
	s_nop 0
	global_load_lds_dwordx4 v[200:201], off
	s_waitcnt vmcnt(8)
	s_waitcnt lgkmcnt(0)
	s_barrier
	s_setprio 1
	s_waitcnt lgkmcnt(0)
	v_mfma_f32_16x16x32_bf16 v[68:71], v[132:135], v[184:187], v[68:71]
	v_mfma_f32_16x16x32_bf16 v[60:63], v[160:163], v[184:187], v[60:63]
	v_mfma_f32_16x16x32_bf16 v[48:51], v[132:135], v[192:195], v[48:51]
	v_mfma_f32_16x16x32_bf16 v[44:47], v[160:163], v[192:195], v[44:47]
	v_mfma_f32_16x16x32_bf16 v[32:35], v[132:135], v[214:217], v[32:35]
	v_mfma_f32_16x16x32_bf16 v[28:31], v[160:163], v[214:217], v[28:31]
	v_mfma_f32_16x16x32_bf16 v[16:19], v[132:135], v[222:225], v[16:19]
	v_mfma_f32_16x16x32_bf16 v[12:15], v[160:163], v[222:225], v[12:15]
	v_mfma_f32_16x16x32_bf16 v[68:71], v[140:143], v[188:191], v[68:71]
	v_mfma_f32_16x16x32_bf16 v[60:63], v[164:167], v[188:191], v[60:63]
	v_mfma_f32_16x16x32_bf16 v[48:51], v[140:143], v[196:199], v[48:51]
	v_mfma_f32_16x16x32_bf16 v[44:47], v[164:167], v[196:199], v[44:47]
	v_mfma_f32_16x16x32_bf16 v[32:35], v[140:143], v[218:221], v[32:35]
	v_mfma_f32_16x16x32_bf16 v[28:31], v[164:167], v[218:221], v[28:31]
	v_mfma_f32_16x16x32_bf16 v[16:19], v[140:143], v[226:229], v[16:19]
	v_mfma_f32_16x16x32_bf16 v[12:15], v[164:167], v[226:229], v[12:15]
	s_setprio 0
	s_setprio 1
	v_mfma_f32_16x16x32_bf16 v[56:59], v[168:171], v[184:187], v[56:59]
	v_mfma_f32_16x16x32_bf16 v[52:55], v[176:179], v[184:187], v[52:55]
	v_mfma_f32_16x16x32_bf16 v[40:43], v[168:171], v[192:195], v[40:43]
	v_mfma_f32_16x16x32_bf16 v[36:39], v[176:179], v[192:195], v[36:39]
	v_mfma_f32_16x16x32_bf16 v[24:27], v[168:171], v[214:217], v[24:27]
	v_mfma_f32_16x16x32_bf16 v[20:23], v[176:179], v[214:217], v[20:23]
	v_mfma_f32_16x16x32_bf16 v[8:11], v[168:171], v[222:225], v[8:11]
	v_mfma_f32_16x16x32_bf16 v[4:7], v[176:179], v[222:225], v[4:7]
	v_mfma_f32_16x16x32_bf16 v[56:59], v[172:175], v[188:191], v[56:59]
	v_mfma_f32_16x16x32_bf16 v[52:55], v[180:183], v[188:191], v[52:55]
	v_mfma_f32_16x16x32_bf16 v[40:43], v[172:175], v[196:199], v[40:43]
	v_mfma_f32_16x16x32_bf16 v[36:39], v[180:183], v[196:199], v[36:39]
	v_mfma_f32_16x16x32_bf16 v[24:27], v[172:175], v[218:221], v[24:27]
	v_mfma_f32_16x16x32_bf16 v[20:23], v[180:183], v[218:221], v[20:23]
	v_mfma_f32_16x16x32_bf16 v[8:11], v[172:175], v[226:229], v[8:11]
	v_mfma_f32_16x16x32_bf16 v[4:7], v[180:183], v[226:229], v[4:7]
	s_setprio 0
	s_barrier
	s_add_i32 s77, s77, 2
	s_add_u32 s70, s70, 0x100
	s_addc_u32 s71, s71, 0

; #define PG8_STAGE(bufoff, gbase, voff) do { _Pragma("unroll") for (int _i = 0; _i < 2; ++_i) \
;         __builtin_amdgcn_global_load_lds((const unsigned*)((const char*)(gbase) + (voff)[_i]), (LAS unsigned*)(lds + (bufoff) + ldsw + _i * 8192), 16, 0, 0); } while (0)
; #define PG8_WAIT_V(n) asm volatile("s_waitcnt vmcnt(" #n ")" ::: "memory")
; #define PG8_BAR __builtin_amdgcn_s_barrier()
; template <class Epi>
; __device__ __forceinline__ void gemm_phase(LAS unsigned char* lds, const Gemm g, const int G, const int cidx, const Epi& E) {
;     ...
;     f32x4 acc[2][2][4][2];
; #pragma unroll
;     for (int a = 0; a < 2; ++a)
; #pragma unroll
;         for (int b = 0; b < 2; ++b)
; #pragma unroll
;             for (int m = 0; m < 4; ++m)
; #pragma unroll
;                 for (int n = 0; n < 2; ++n) acc[a][b][m][n] = ZERO4;
;     bf16x8 At[4][2], B0[2][2], B1[2][2];
;     const char* cA = PG8_ABASE(cur); const char* cB = (const char*)g.Bt + (size_t)cur.pn * tstep;
;     PG8_STAGE(PG8_SB(0, 0), cB, voffB); PG8_STAGE(PG8_SB(0, 1), cB + hstep, voffB); PG8_STAGE(PG8_SA(0, 0), cA, voffA); PG8_STAGE(PG8_SA(0, 1), cA + hstep, voffA);
;     if (wr == 1) PG8_BAR;
;     PG8_WAIT_V(2); PG8_BAR;
;     PG8_STAGE(PG8_SB(1, 0), cB + kstep, voffB); PG8_STAGE(PG8_SA(1, 0), cA + kstep, voffA); PG8_STAGE(PG8_SB(1, 1), cB + hstep + kstep, voffB);
;     PG8_WAIT_V(6); PG8_BAR;
.LBB0_438:
	v_and_b32_e32 v158, 15, v156
	v_and_b32_e32 v17, 48, v156
	v_lshlrev_b32_e32 v18, 2, v156
	s_sext_i32_i8 s14, s4
	s_and_b32 s69, s15, 3
	s_lshl_b32 s4, s36, 13
	v_lshl_or_b32 v17, v158, 6, v17
	v_and_b32_e32 v18, 32, v18
	s_add_i32 m0, s71, 0x18000
	v_lshl_add_u64 v[8:9], v[8:9], 0, s[46:47]
	s_lshl_b32 s39, s36, 6
	v_bitop3_b32 v19, v17, s4, v18 bitop3:0xde
	s_lshl_b32 s4, s69, 12
	s_waitcnt vmcnt(2)
	s_barrier
	global_load_lds_dwordx4 v[8:9], off
	v_lshl_add_u64 v[6:7], v[6:7], 0, s[46:47]
	s_add_i32 m0, s71, 0x1a000
	s_add_i32 s75, s71, 0x8000
	s_add_i32 s76, s71, 0xa000
	v_bitop3_b32 v157, v17, s4, v18 bitop3:0xde
	global_load_lds_dwordx4 v[6:7], off
	v_lshl_add_u64 v[4:5], v[4:5], 0, s[46:47]
	s_mov_b32 m0, s75
	s_add_u32 s4, s24, 0xb0080
	global_load_lds_dwordx4 v[4:5], off
	v_lshl_add_u64 v[0:1], v[0:1], 0, s[46:47]
	s_mov_b32 m0, s76
	s_addc_u32 s5, s25, 0
	global_load_lds_dwordx4 v[0:1], off
	s_add_i32 m0, s71, 0x1c000
	v_lshl_add_u64 v[0:1], s[4:5], 0, v[146:147]
	global_load_lds_dwordx4 v[0:1], off
	v_lshl_add_u64 v[0:1], s[4:5], 0, v[148:149]
	s_add_i32 m0, s71, 0x1e000
	s_movk_i32 s6, 0xb00
	global_load_lds_dwordx4 v[0:1], off
	v_lshrrev_b32_e32 v1, 1, v13
	v_mul_lo_u32 v0, v15, s6
	s_mov_b32 s7, 0xb000
	v_mad_u64_u32 v[0:1], s[4:5], v1, s7, v[0:1]
	v_or_b32_e32 v0, v0, v14
	v_add_lshl_u32 v150, v0, v16, 1
	v_lshrrev_b32_e32 v1, 1, v3
	v_mul_lo_u32 v0, v11, s6
	v_mad_u64_u32 v[0:1], s[4:5], v1, s7, v[0:1]
	s_waitcnt vmcnt(6)
	v_or_b32_e32 v0, v0, v10
	v_mov_b32_e32 v3, v2
	v_add_lshl_u32 v152, v0, v12, 1
	v_mov_b32_e32 v0, v2
	v_mov_b32_e32 v1, v2
	v_add_u32_e32 v159, 0, v19
	v_or_b32_e32 v145, s39, v158
	v_mov_b32_e32 v151, v2
	v_mov_b32_e32 v153, v2
	s_mov_b32 s79, 0
	s_barrier

; #define PG8_STAGE(bufoff, gbase, voff) do { _Pragma("unroll") for (int _i = 0; _i < 2; ++_i) \
;         __builtin_amdgcn_global_load_lds((const unsigned*)((const char*)(gbase) + (voff)[_i]), (LAS unsigned*)(lds + (bufoff) + ldsw + _i * 8192), 16, 0, 0); } while (0)
; #define PG8_LDA(dst, b, h) do { _Pragma("unroll") for (int m = 0; m < 4; ++m) _Pragma("unroll") for (int k = 0; k < 2; ++k) dst[m][k] = *(const LAS bf16x8*)(lds + PG8_SA(b, h) + aoff + m * 2048 + k * 1024); } while (0)
; #define PG8_LDB(dst, b, h) do { _Pragma("unroll") for (int n = 0; n < 2; ++n) _Pragma("unroll") for (int k = 0; k < 2; ++k) dst[n][k] = *(const LAS bf16x8*)(lds + PG8_SB(b, h) + boff + n * 2048 + k * 1024); } while (0)
; #define PG8_MMA(ai, bj, At, Bt) do { __builtin_amdgcn_s_setprio(1); _Pragma("unroll") for (int m = 0; m < 4; ++m) _Pragma("unroll") for (int n = 0; n < 2; ++n) _Pragma("unroll") for (int k = 0; k < 2; ++k) \
;         acc[ai][bj][m][n] = __builtin_amdgcn_mfma_f32_16x16x32_bf16(Bt[n][k], At[m][k], acc[ai][bj][m][n], 0, 0, 0); __builtin_amdgcn_s_setprio(0); } while (0)
; #define PG8_WAIT_V(n) asm volatile("s_waitcnt vmcnt(" #n ")" ::: "memory")
; #define PG8_WAIT_L(n) asm volatile("s_waitcnt lgkmcnt(" #n ")" ::: "memory")
; #define PG8_BAR __builtin_amdgcn_s_barrier()
; #define PG8_SCHED __builtin_amdgcn_sched_barrier(0)
; template <class Epi>
; __device__ __forceinline__ void gemm_phase(LAS unsigned char* lds, const Gemm g, const int G, const int cidx, const Epi& E) {
;     ...
;         for (int t = 0; t < nt; t += 2) {
;             const bool last = (t == nt - 2);
;             const char* a1 = cA + (size_t)(t + 1) * kstep;
;             const char* a2 = last ? nA : cA + (size_t)(t + 2) * kstep; const char* b2 = last ? nB : cB + (size_t)(t + 2) * kstep;
;             const char* a3 = a2 + kstep; const char* b3 = b2 + kstep;
;             PG8_LDB(B0, 0, 0); PG8_LDB(B1, 0, 1); PG8_SCHED; PG8_LDA(At, 0, 0); PG8_STAGE(PG8_SA(1, 1), a1 + hstep, voffA);
;             PG8_WAIT_V(8); PG8_WAIT_L(0); PG8_BAR; PG8_MMA(0, 0, At, B0); PG8_MMA(0, 1, At, B1); PG8_BAR; PG8_SCHED;
;             PG8_LDA(At, 0, 1); PG8_STAGE(PG8_SB(0, 0), b2, voffB); PG8_STAGE(PG8_SB(0, 1), b2 + hstep, voffB); PG8_STAGE(PG8_SA(0, 0), a2, voffA);
;             PG8_WAIT_V(8); PG8_WAIT_L(0); PG8_BAR; PG8_MMA(1, 0, At, B0); PG8_MMA(1, 1, At, B1); PG8_BAR; PG8_SCHED;
.LBB0_449:
	s_add_u32 s43, s24, 0x100
	s_addc_u32 s44, s25, 0
	s_add_u32 s24, s10, 0xb0080
	s_addc_u32 s25, s11, 0
	v_lshl_add_u64 v[0:1], s[24:25], 0, v[150:151]
	v_lshl_add_u64 v[154:155], s[24:25], 0, v[152:153]
	s_mov_b32 s45, -2
	s_mov_b64 s[24:25], 0
	s_add_u32 s26, s10, s24
	s_addc_u32 s27, s11, s25
	s_add_u32 s26, s26, 0x100
	s_addc_u32 s27, s27, 0
	s_add_u32 s68, s43, s24
	s_addc_u32 s77, s44, s25
	s_add_i32 s83, 0, 0x10000
	s_cmpk_eq_i32 s24, 0x1500
	s_cselect_b32 s29, s21, s27
	s_cselect_b32 s28, s20, s26
	v_add_u32_e32 v3, s83, v157
	s_cselect_b32 s27, s9, s77
	s_cselect_b32 s26, s8, s68
	s_add_i32 s68, 0, 0x14000
	ds_read_b128 v[132:135], v3
	ds_read_b128 v[140:143], v3 offset:1024
	ds_read_b128 v[160:163], v3 offset:2048
	ds_read_b128 v[164:167], v3 offset:3072
	v_add_u32_e32 v3, s68, v157
	ds_read_b128 v[168:171], v3
	ds_read_b128 v[172:175], v3 offset:1024
	ds_read_b128 v[176:179], v3 offset:2048
	ds_read_b128 v[180:183], v3 offset:3072
	v_lshl_add_u64 v[200:201], v[154:155], 0, s[24:25]
	s_add_i32 m0, s71, 0xc000
	ds_read_b128 v[184:187], v159
	ds_read_b128 v[188:191], v159 offset:1024
	ds_read_b128 v[192:195], v159 offset:2048
	ds_read_b128 v[196:199], v159 offset:3072
	ds_read_b128 v[214:217], v159 offset:4096
	ds_read_b128 v[218:221], v159 offset:5120
	ds_read_b128 v[222:225], v159 offset:6144
	ds_read_b128 v[226:229], v159 offset:7168
	global_load_lds_dwordx4 v[200:201], off
	v_lshl_add_u64 v[200:201], v[0:1], 0, s[24:25]
	s_add_i32 m0, s71, 0xe000
	s_nop 0
	global_load_lds_dwordx4 v[200:201], off
	s_waitcnt vmcnt(8)
	s_waitcnt lgkmcnt(0)
	s_barrier
	s_setprio 1
	s_waitcnt lgkmcnt(0)
	v_mfma_f32_16x16x32_bf16 v[100:103], v[132:135], v[184:187], 0
	v_mfma_f32_16x16x32_bf16 v[108:111], v[160:163], v[184:187], 0
	v_mfma_f32_16x16x32_bf16 v[120:123], v[132:135], v[192:195], 0
	v_mfma_f32_16x16x32_bf16 v[128:131], v[160:163], v[192:195], 0
	v_mfma_f32_16x16x32_bf16 v[96:99], v[132:135], v[214:217], 0
	v_mfma_f32_16x16x32_bf16 v[92:95], v[160:163], v[214:217], 0
	v_mfma_f32_16x16x32_bf16 v[80:83], v[132:135], v[222:225], 0
	v_mfma_f32_16x16x32_bf16 v[76:79], v[160:163], v[222:225], 0
	v_mfma_f32_16x16x32_bf16 v[100:103], v[140:143], v[188:191], v[100:103]
	v_mfma_f32_16x16x32_bf16 v[108:111], v[164:167], v[188:191], v[108:111]
	v_mfma_f32_16x16x32_bf16 v[120:123], v[140:143], v[196:199], v[120:123]
	v_mfma_f32_16x16x32_bf16 v[128:131], v[164:167], v[196:199], v[128:131]
	v_mfma_f32_16x16x32_bf16 v[96:99], v[140:143], v[218:221], v[96:99]
	v_mfma_f32_16x16x32_bf16 v[92:95], v[164:167], v[218:221], v[92:95]
	v_mfma_f32_16x16x32_bf16 v[80:83], v[140:143], v[226:229], v[80:83]
	v_mfma_f32_16x16x32_bf16 v[76:79], v[164:167], v[226:229], v[76:79]
	s_setprio 0
	s_setprio 1
	v_mfma_f32_16x16x32_bf16 v[116:119], v[168:171], v[184:187], 0
	v_mfma_f32_16x16x32_bf16 v[124:127], v[176:179], v[184:187], 0
	v_mfma_f32_16x16x32_bf16 v[112:115], v[168:171], v[192:195], 0
	v_mfma_f32_16x16x32_bf16 v[104:107], v[176:179], v[192:195], 0
	v_mfma_f32_16x16x32_bf16 v[88:91], v[168:171], v[214:217], 0
	v_mfma_f32_16x16x32_bf16 v[84:87], v[176:179], v[214:217], 0
	v_mfma_f32_16x16x32_bf16 v[72:75], v[168:171], v[222:225], 0
	v_mfma_f32_16x16x32_bf16 v[68:71], v[176:179], v[222:225], 0
	v_mfma_f32_16x16x32_bf16 v[116:119], v[172:175], v[188:191], v[116:119]
	v_mfma_f32_16x16x32_bf16 v[124:127], v[180:183], v[188:191], v[124:127]
	v_mfma_f32_16x16x32_bf16 v[112:115], v[172:175], v[196:199], v[112:115]
	v_mfma_f32_16x16x32_bf16 v[104:107], v[180:183], v[196:199], v[104:107]
	v_mfma_f32_16x16x32_bf16 v[88:91], v[172:175], v[218:221], v[88:91]
	v_mfma_f32_16x16x32_bf16 v[84:87], v[180:183], v[218:221], v[84:87]
	v_mfma_f32_16x16x32_bf16 v[72:75], v[172:175], v[226:229], v[72:75]
	v_mfma_f32_16x16x32_bf16 v[68:71], v[180:183], v[226:229], v[68:71]
	s_setprio 0
	s_barrier
	s_add_i32 s77, s83, s70
	v_lshl_add_u64 v[200:201], s[26:27], 0, v[146:147]
	s_mov_b32 m0, s77
	ds_read_b128 v[184:187], v159 offset:16384
	ds_read_b128 v[188:191], v159 offset:17408
	ds_read_b128 v[192:195], v159 offset:18432
	ds_read_b128 v[196:199], v159 offset:19456
	ds_read_b128 v[214:217], v159 offset:20480
	ds_read_b128 v[218:221], v159 offset:21504
	ds_read_b128 v[222:225], v159 offset:22528
	ds_read_b128 v[226:229], v159 offset:23552
	global_load_lds_dwordx4 v[200:201], off
	s_add_i32 m0, s77, 0x2000
	s_add_u32 s86, s26, 0xb0000
	v_lshl_add_u64 v[230:231], s[26:27], 0, v[148:149]
	s_addc_u32 s87, s27, 0
	s_add_i32 s68, s68, s70
	global_load_lds_dwordx4 v[230:231], off
	v_lshl_add_u64 v[232:233], s[86:87], 0, v[146:147]
	s_mov_b32 m0, s68
	v_lshl_add_u64 v[234:235], s[28:29], 0, v[148:149]
	global_load_lds_dwordx4 v[232:233], off
	v_lshl_add_u64 v[232:233], s[86:87], 0, v[148:149]
	s_add_i32 m0, s68, 0x2000
	s_nop 0
	global_load_lds_dwordx4 v[232:233], off
	v_lshl_add_u64 v[232:233], s[28:29], 0, v[146:147]
	s_mov_b32 m0, s71
	s_nop 0
	global_load_lds_dwordx4 v[232:233], off
	s_mov_b32 m0, s72
	s_nop 0
	global_load_lds_dwordx4 v[234:235], off
	s_waitcnt vmcnt(8)
	s_waitcnt lgkmcnt(0)
	s_barrier
; #define PG8_STAGE(bufoff, gbase, voff) do { _Pragma("unroll") for (int _i = 0; _i < 2; ++_i) \
;         __builtin_amdgcn_global_load_lds((const unsigned*)((const char*)(gbase) + (voff)[_i]), (LAS unsigned*)(lds + (bufoff) + ldsw + _i * 8192), 16, 0, 0); } while (0)
; #define PG8_LDA(dst, b, h) do { _Pragma("unroll") for (int m = 0; m < 4; ++m) _Pragma("unroll") for (int k = 0; k < 2; ++k) dst[m][k] = *(const LAS bf16x8*)(lds + PG8_SA(b, h) + aoff + m * 2048 + k * 1024); } while (0)
; #define PG8_LDB(dst, b, h) do { _Pragma("unroll") for (int n = 0; n < 2; ++n) _Pragma("unroll") for (int k = 0; k < 2; ++k) dst[n][k] = *(const LAS bf16x8*)(lds + PG8_SB(b, h) + boff + n * 2048 + k * 1024); } while (0)
; #define PG8_MMA(ai, bj, At, Bt) do { __builtin_amdgcn_s_setprio(1); _Pragma("unroll") for (int m = 0; m < 4; ++m) _Pragma("unroll") for (int n = 0; n < 2; ++n) _Pragma("unroll") for (int k = 0; k < 2; ++k) \
;         acc[ai][bj][m][n] = __builtin_amdgcn_mfma_f32_16x16x32_bf16(Bt[n][k], At[m][k], acc[ai][bj][m][n], 0, 0, 0); __builtin_amdgcn_s_setprio(0); } while (0)
; #define PG8_WAIT_V(n) asm volatile("s_waitcnt vmcnt(" #n ")" ::: "memory")
; #define PG8_WAIT_L(n) asm volatile("s_waitcnt lgkmcnt(" #n ")" ::: "memory")
; #define PG8_BAR __builtin_amdgcn_s_barrier()
; #define PG8_SCHED __builtin_amdgcn_sched_barrier(0)
; template <class Epi>
; __device__ __forceinline__ void gemm_phase(LAS unsigned char* lds, const Gemm g, const int G, const int cidx, const Epi& E) {
;     ...
;             PG8_WAIT_V(8); PG8_WAIT_L(0); PG8_BAR; PG8_MMA(1, 0, At, B0); PG8_MMA(1, 1, At, B1); PG8_BAR; PG8_SCHED;
;             PG8_LDB(B0, 1, 0); PG8_LDB(B1, 1, 1); PG8_SCHED; PG8_LDA(At, 1, 0); PG8_STAGE(PG8_SA(0, 1), a2 + hstep, voffA);
;             PG8_WAIT_V(8); PG8_WAIT_L(0); PG8_BAR; PG8_MMA(0, 0, At, B0); PG8_MMA(0, 1, At, B1); PG8_BAR; PG8_SCHED;
	s_setprio 1
	s_waitcnt lgkmcnt(0)
	v_mfma_f32_16x16x32_bf16 v[64:67], v[132:135], v[184:187], 0
	v_mfma_f32_16x16x32_bf16 v[60:63], v[160:163], v[184:187], 0
	v_mfma_f32_16x16x32_bf16 v[48:51], v[132:135], v[192:195], 0
	v_mfma_f32_16x16x32_bf16 v[44:47], v[160:163], v[192:195], 0
	v_mfma_f32_16x16x32_bf16 v[32:35], v[132:135], v[214:217], 0
	v_mfma_f32_16x16x32_bf16 v[28:31], v[160:163], v[214:217], 0
	v_mfma_f32_16x16x32_bf16 v[16:19], v[132:135], v[222:225], 0
	v_mfma_f32_16x16x32_bf16 v[12:15], v[160:163], v[222:225], 0
	v_mfma_f32_16x16x32_bf16 v[64:67], v[140:143], v[188:191], v[64:67]
	v_mfma_f32_16x16x32_bf16 v[60:63], v[164:167], v[188:191], v[60:63]
	v_mfma_f32_16x16x32_bf16 v[48:51], v[140:143], v[196:199], v[48:51]
	v_mfma_f32_16x16x32_bf16 v[44:47], v[164:167], v[196:199], v[44:47]
	v_mfma_f32_16x16x32_bf16 v[32:35], v[140:143], v[218:221], v[32:35]
	v_mfma_f32_16x16x32_bf16 v[28:31], v[164:167], v[218:221], v[28:31]
	v_mfma_f32_16x16x32_bf16 v[16:19], v[140:143], v[226:229], v[16:19]
	v_mfma_f32_16x16x32_bf16 v[12:15], v[164:167], v[226:229], v[12:15]
	s_setprio 0
	s_setprio 1
	v_mfma_f32_16x16x32_bf16 v[56:59], v[168:171], v[184:187], 0
	v_mfma_f32_16x16x32_bf16 v[52:55], v[176:179], v[184:187], 0
	v_mfma_f32_16x16x32_bf16 v[40:43], v[168:171], v[192:195], 0
	v_mfma_f32_16x16x32_bf16 v[36:39], v[176:179], v[192:195], 0
	v_mfma_f32_16x16x32_bf16 v[24:27], v[168:171], v[214:217], 0
	v_mfma_f32_16x16x32_bf16 v[20:23], v[176:179], v[214:217], 0
	v_mfma_f32_16x16x32_bf16 v[8:11], v[168:171], v[222:225], 0
	v_mfma_f32_16x16x32_bf16 v[4:7], v[176:179], v[222:225], 0
	v_mfma_f32_16x16x32_bf16 v[56:59], v[172:175], v[188:191], v[56:59]
	v_mfma_f32_16x16x32_bf16 v[52:55], v[180:183], v[188:191], v[52:55]
	v_mfma_f32_16x16x32_bf16 v[40:43], v[172:175], v[196:199], v[40:43]
	v_mfma_f32_16x16x32_bf16 v[36:39], v[180:183], v[196:199], v[36:39]
	v_mfma_f32_16x16x32_bf16 v[24:27], v[172:175], v[218:221], v[24:27]
	v_mfma_f32_16x16x32_bf16 v[20:23], v[180:183], v[218:221], v[20:23]
	v_mfma_f32_16x16x32_bf16 v[8:11], v[172:175], v[226:229], v[8:11]
	v_mfma_f32_16x16x32_bf16 v[4:7], v[180:183], v[226:229], v[4:7]
	s_setprio 0
	s_barrier
	s_add_i32 s68, 0, 0x18000
	v_add_u32_e32 v3, s68, v157
	s_add_i32 s77, 0, 0x1c000
	ds_read_b128 v[132:135], v3
	ds_read_b128 v[140:143], v3 offset:1024
	ds_read_b128 v[160:163], v3 offset:2048
	ds_read_b128 v[164:167], v3 offset:3072
	v_add_u32_e32 v3, s77, v157
	ds_read_b128 v[168:171], v3
	ds_read_b128 v[172:175], v3 offset:1024
	ds_read_b128 v[176:179], v3 offset:2048
	ds_read_b128 v[180:183], v3 offset:3072
	s_add_u32 s28, s28, 0xb0000
	s_addc_u32 s29, s29, 0
	s_mov_b32 m0, s73
	v_lshl_add_u64 v[236:237], s[28:29], 0, v[146:147]
	ds_read_b128 v[184:187], v159 offset:32768
	ds_read_b128 v[188:191], v159 offset:33792
	ds_read_b128 v[192:195], v159 offset:34816
	ds_read_b128 v[196:199], v159 offset:35840
	ds_read_b128 v[214:217], v159 offset:36864
	ds_read_b128 v[218:221], v159 offset:37888
	ds_read_b128 v[222:225], v159 offset:38912
	ds_read_b128 v[226:229], v159 offset:39936
	global_load_lds_dwordx4 v[236:237], off
	v_lshl_add_u64 v[236:237], s[28:29], 0, v[148:149]
	s_mov_b32 m0, s74
	s_nop 0
	global_load_lds_dwordx4 v[236:237], off
	s_waitcnt vmcnt(8)
	s_waitcnt lgkmcnt(0)
	s_barrier
	s_setprio 1
	s_waitcnt lgkmcnt(0)
	v_mfma_f32_16x16x32_bf16 v[100:103], v[132:135], v[184:187], v[100:103]
	v_mfma_f32_16x16x32_bf16 v[108:111], v[160:163], v[184:187], v[108:111]
	v_mfma_f32_16x16x32_bf16 v[120:123], v[132:135], v[192:195], v[120:123]
	v_mfma_f32_16x16x32_bf16 v[128:131], v[160:163], v[192:195], v[128:131]
	v_mfma_f32_16x16x32_bf16 v[96:99], v[132:135], v[214:217], v[96:99]
	v_mfma_f32_16x16x32_bf16 v[92:95], v[160:163], v[214:217], v[92:95]
	v_mfma_f32_16x16x32_bf16 v[80:83], v[132:135], v[222:225], v[80:83]
	v_mfma_f32_16x16x32_bf16 v[76:79], v[160:163], v[222:225], v[76:79]
	v_mfma_f32_16x16x32_bf16 v[100:103], v[140:143], v[188:191], v[100:103]
	v_mfma_f32_16x16x32_bf16 v[108:111], v[164:167], v[188:191], v[108:111]
	v_mfma_f32_16x16x32_bf16 v[120:123], v[140:143], v[196:199], v[120:123]
	v_mfma_f32_16x16x32_bf16 v[128:131], v[164:167], v[196:199], v[128:131]
	v_mfma_f32_16x16x32_bf16 v[96:99], v[140:143], v[218:221], v[96:99]
	v_mfma_f32_16x16x32_bf16 v[92:95], v[164:167], v[218:221], v[92:95]
	v_mfma_f32_16x16x32_bf16 v[80:83], v[140:143], v[226:229], v[80:83]
	v_mfma_f32_16x16x32_bf16 v[76:79], v[164:167], v[226:229], v[76:79]
	s_setprio 0
	s_setprio 1
	v_mfma_f32_16x16x32_bf16 v[116:119], v[168:171], v[184:187], v[116:119]
	v_mfma_f32_16x16x32_bf16 v[124:127], v[176:179], v[184:187], v[124:127]
	v_mfma_f32_16x16x32_bf16 v[112:115], v[168:171], v[192:195], v[112:115]
	v_mfma_f32_16x16x32_bf16 v[104:107], v[176:179], v[192:195], v[104:107]
	v_mfma_f32_16x16x32_bf16 v[88:91], v[168:171], v[214:217], v[88:91]
	v_mfma_f32_16x16x32_bf16 v[84:87], v[176:179], v[214:217], v[84:87]
	v_mfma_f32_16x16x32_bf16 v[72:75], v[168:171], v[222:225], v[72:75]
	v_mfma_f32_16x16x32_bf16 v[68:71], v[176:179], v[222:225], v[68:71]
	v_mfma_f32_16x16x32_bf16 v[116:119], v[172:175], v[188:191], v[116:119]
	v_mfma_f32_16x16x32_bf16 v[124:127], v[180:183], v[188:191], v[124:127]
	v_mfma_f32_16x16x32_bf16 v[112:115], v[172:175], v[196:199], v[112:115]
	v_mfma_f32_16x16x32_bf16 v[104:107], v[180:183], v[196:199], v[104:107]
	v_mfma_f32_16x16x32_bf16 v[88:91], v[172:175], v[218:221], v[88:91]
	v_mfma_f32_16x16x32_bf16 v[84:87], v[180:183], v[218:221], v[84:87]
	v_mfma_f32_16x16x32_bf16 v[72:75], v[172:175], v[226:229], v[72:75]
	v_mfma_f32_16x16x32_bf16 v[68:71], v[180:183], v[226:229], v[68:71]
	s_setprio 0
	s_barrier
; #define PG8_STAGE(bufoff, gbase, voff) do { _Pragma("unroll") for (int _i = 0; _i < 2; ++_i) \
;         __builtin_amdgcn_global_load_lds((const unsigned*)((const char*)(gbase) + (voff)[_i]), (LAS unsigned*)(lds + (bufoff) + ldsw + _i * 8192), 16, 0, 0); } while (0)
; #define PG8_LDA(dst, b, h) do { _Pragma("unroll") for (int m = 0; m < 4; ++m) _Pragma("unroll") for (int k = 0; k < 2; ++k) dst[m][k] = *(const LAS bf16x8*)(lds + PG8_SA(b, h) + aoff + m * 2048 + k * 1024); } while (0)
; #define PG8_MMA(ai, bj, At, Bt) do { __builtin_amdgcn_s_setprio(1); _Pragma("unroll") for (int m = 0; m < 4; ++m) _Pragma("unroll") for (int n = 0; n < 2; ++n) _Pragma("unroll") for (int k = 0; k < 2; ++k) \
;         acc[ai][bj][m][n] = __builtin_amdgcn_mfma_f32_16x16x32_bf16(Bt[n][k], At[m][k], acc[ai][bj][m][n], 0, 0, 0); __builtin_amdgcn_s_setprio(0); } while (0)
; #define PG8_WAIT_V(n) asm volatile("s_waitcnt vmcnt(" #n ")" ::: "memory")
; #define PG8_WAIT_L(n) asm volatile("s_waitcnt lgkmcnt(" #n ")" ::: "memory")
; #define PG8_BAR __builtin_amdgcn_s_barrier()
; #define PG8_SCHED __builtin_amdgcn_sched_barrier(0)
; template <class Epi>
; __device__ __forceinline__ void gemm_phase(LAS unsigned char* lds, const Gemm g, const int G, const int cidx, const Epi& E) {
;     ...
;             PG8_LDA(At, 1, 1); PG8_STAGE(PG8_SB(1, 0), b3, voffB); PG8_STAGE(PG8_SB(1, 1), b3 + hstep, voffB); PG8_STAGE(PG8_SA(1, 0), a3, voffA);
;             PG8_WAIT_V(8); PG8_WAIT_L(0); PG8_BAR; PG8_MMA(1, 0, At, B0); PG8_MMA(1, 1, At, B1); PG8_BAR; PG8_SCHED;
	s_add_i32 s28, s68, s70
	v_lshl_add_u64 v[200:201], v[200:201], 0, s[46:47]
	s_mov_b32 m0, s28
	ds_read_b128 v[184:187], v159 offset:49152
	ds_read_b128 v[188:191], v159 offset:50176
	ds_read_b128 v[192:195], v159 offset:51200
	ds_read_b128 v[196:199], v159 offset:52224
	ds_read_b128 v[214:217], v159 offset:53248
	ds_read_b128 v[218:221], v159 offset:54272
	ds_read_b128 v[222:225], v159 offset:55296
	ds_read_b128 v[226:229], v159 offset:56320
	global_load_lds_dwordx4 v[200:201], off
	s_add_i32 m0, s28, 0x2000
	s_add_u32 s26, s26, 0xb0080
	v_lshl_add_u64 v[200:201], v[230:231], 0, s[46:47]
	s_addc_u32 s27, s27, 0
	s_add_i32 s28, s77, s70
	global_load_lds_dwordx4 v[200:201], off
	v_lshl_add_u64 v[200:201], s[26:27], 0, v[146:147]
	s_mov_b32 m0, s28
	s_nop 0
	global_load_lds_dwordx4 v[200:201], off
	v_lshl_add_u64 v[200:201], s[26:27], 0, v[148:149]
	s_add_i32 m0, s28, 0x2000
	s_nop 0
	global_load_lds_dwordx4 v[200:201], off
	v_lshl_add_u64 v[200:201], v[232:233], 0, s[46:47]
	s_mov_b32 m0, s75
	s_nop 0
	global_load_lds_dwordx4 v[200:201], off
	v_lshl_add_u64 v[200:201], v[234:235], 0, s[46:47]
	s_mov_b32 m0, s76
	s_nop 0
	global_load_lds_dwordx4 v[200:201], off
	s_waitcnt vmcnt(8)
	s_waitcnt lgkmcnt(0)
	s_barrier
	s_setprio 1
	s_waitcnt lgkmcnt(0)
	v_mfma_f32_16x16x32_bf16 v[64:67], v[132:135], v[184:187], v[64:67]
	v_mfma_f32_16x16x32_bf16 v[60:63], v[160:163], v[184:187], v[60:63]
	v_mfma_f32_16x16x32_bf16 v[48:51], v[132:135], v[192:195], v[48:51]
	v_mfma_f32_16x16x32_bf16 v[44:47], v[160:163], v[192:195], v[44:47]
	v_mfma_f32_16x16x32_bf16 v[32:35], v[132:135], v[214:217], v[32:35]
	v_mfma_f32_16x16x32_bf16 v[28:31], v[160:163], v[214:217], v[28:31]
	v_mfma_f32_16x16x32_bf16 v[16:19], v[132:135], v[222:225], v[16:19]
	v_mfma_f32_16x16x32_bf16 v[12:15], v[160:163], v[222:225], v[12:15]
	v_mfma_f32_16x16x32_bf16 v[64:67], v[140:143], v[188:191], v[64:67]
	v_mfma_f32_16x16x32_bf16 v[60:63], v[164:167], v[188:191], v[60:63]
	v_mfma_f32_16x16x32_bf16 v[48:51], v[140:143], v[196:199], v[48:51]
	v_mfma_f32_16x16x32_bf16 v[44:47], v[164:167], v[196:199], v[44:47]
	v_mfma_f32_16x16x32_bf16 v[32:35], v[140:143], v[218:221], v[32:35]
	v_mfma_f32_16x16x32_bf16 v[28:31], v[164:167], v[218:221], v[28:31]
	v_mfma_f32_16x16x32_bf16 v[16:19], v[140:143], v[226:229], v[16:19]
	v_mfma_f32_16x16x32_bf16 v[12:15], v[164:167], v[226:229], v[12:15]
	s_setprio 0
	s_setprio 1
	v_mfma_f32_16x16x32_bf16 v[56:59], v[168:171], v[184:187], v[56:59]
	v_mfma_f32_16x16x32_bf16 v[52:55], v[176:179], v[184:187], v[52:55]
	v_mfma_f32_16x16x32_bf16 v[40:43], v[168:171], v[192:195], v[40:43]
	v_mfma_f32_16x16x32_bf16 v[36:39], v[176:179], v[192:195], v[36:39]
	v_mfma_f32_16x16x32_bf16 v[24:27], v[168:171], v[214:217], v[24:27]
	v_mfma_f32_16x16x32_bf16 v[20:23], v[176:179], v[214:217], v[20:23]
	v_mfma_f32_16x16x32_bf16 v[8:11], v[168:171], v[222:225], v[8:11]
	v_mfma_f32_16x16x32_bf16 v[4:7], v[176:179], v[222:225], v[4:7]
	v_mfma_f32_16x16x32_bf16 v[56:59], v[172:175], v[188:191], v[56:59]
	v_mfma_f32_16x16x32_bf16 v[52:55], v[180:183], v[188:191], v[52:55]
	v_mfma_f32_16x16x32_bf16 v[40:43], v[172:175], v[196:199], v[40:43]
	v_mfma_f32_16x16x32_bf16 v[36:39], v[180:183], v[196:199], v[36:39]
	v_mfma_f32_16x16x32_bf16 v[24:27], v[172:175], v[218:221], v[24:27]
	v_mfma_f32_16x16x32_bf16 v[20:23], v[180:183], v[218:221], v[20:23]
	v_mfma_f32_16x16x32_bf16 v[8:11], v[172:175], v[226:229], v[8:11]
	v_mfma_f32_16x16x32_bf16 v[4:7], v[180:183], v[226:229], v[4:7]
	s_setprio 0
	s_barrier
	s_add_i32 s45, s45, 2
	s_add_u32 s24, s24, 0x100
	s_addc_u32 s25, s25, 0
